# hgrn_c: all fragment/gain/gate loads of a wave task issued up front (one wait) instead of one round trip per MFMA
# speedup vs baseline: 1.0220x; 1.0079x over previous
.LBB0_255:
	s_ashr_i32 s9, s23, 2
	s_add_i32 s8, s9, s84
	s_and_b32 s24, s9, 0xc0
	s_lshl_b32 s9, s9, 6
	s_lshl_b32 s25, s8, 4
	s_and_b32 s9, s9, 0xfc0
	s_and_b32 s26, s22, 48
	s_and_b32 s25, s25, 0xfffff000
	s_or_b32 s9, s26, s9
	s_or_b32 s9, s9, s25
	v_or_b32_e32 v40, s9, v3
	v_ashrrev_i32_e32 v41, 31, v40
	v_lshlrev_b64 v[4:5], 10, v[40:41]
	v_lshl_add_u64 v[4:5], s[0:1], 0, v[4:5]
	s_lshl_b32 s90, s24, 2
	v_lshlrev_b64 v[36:37], 9, v[40:41]
	s_ashr_i32 s9, s8, 31
	v_lshl_add_u64 v[4:5], v[4:5], 0, s[90:91]
	v_lshl_add_u64 v[36:37], s[38:39], 0, v[36:37]
	s_lshl_b32 s90, s24, 1
	s_lshl_b64 s[8:9], s[8:9], 13
	v_lshl_add_u64 v[36:37], v[36:37], 0, s[90:91]
	v_lshl_add_u64 v[52:53], v[22:23], 0, s[8:9]
	v_lshl_add_u64 v[16:17], v[0:1], 2, v[4:5]
	v_lshl_add_u64 v[48:49], v[20:21], 1, v[36:37]
	v_lshl_add_u64 v[54:55], v[52:53], 0, v[26:27]
	v_lshl_add_u64 v[92:93], v[52:53], 0, v[28:29]
	v_lshl_add_u64 v[94:95], v[52:53], 0, v[30:31]
	v_mad_i64_i32 v[120:121], s[8:9], v40, s61, v[32:33]
	v_lshl_add_u64 v[120:121], v[120:121], 0, s[90:91]
	v_lshl_add_u64 v[120:121], v[120:121], 0, v[34:35]
	global_load_dwordx4 v[4:7], v[16:17], off offset:192
	global_load_dwordx4 v[8:11], v[16:17], off offset:128
	global_load_dwordx4 v[12:15], v[16:17], off offset:64
	global_load_dwordx4 v[36:39], v[48:49], off
	global_load_dwordx4 v[56:59], v[48:49], off offset:64
	global_load_dwordx4 v[60:63], v[54:55], off
	global_load_dwordx4 v[64:67], v[54:55], off offset:2048
	global_load_dwordx4 v[68:71], v[92:93], off
	global_load_dwordx4 v[72:75], v[94:95], off
	global_load_dwordx4 v[76:79], v[54:55], off offset:64
	global_load_dwordx4 v[80:83], v[54:55], off offset:2112
	global_load_dwordx4 v[84:87], v[92:93], off offset:64
	global_load_dwordx4 v[88:91], v[94:95], off offset:64
	s_nop 0
	global_load_dwordx4 v[16:19], v[16:17], off
	global_load_dwordx4 v[96:99], v[24:25], off
	global_load_dwordx4 v[100:103], v[24:25], off offset:64
	global_load_dwordx4 v[104:107], v[24:25], off offset:128
	global_load_dwordx4 v[108:111], v[24:25], off offset:192
	global_load_dwordx2 v[112:113], v[120:121], off offset:1536
	global_load_dwordx2 v[114:115], v[120:121], off offset:1568
	global_load_dwordx2 v[116:117], v[120:121], off offset:1600
	global_load_dwordx2 v[118:119], v[120:121], off offset:1632
	s_waitcnt vmcnt(8)
	v_mfma_f32_16x16x32_bf16 v[16:19], v[60:63], v[36:39], v[16:19]
	v_mfma_f32_16x16x32_bf16 v[12:15], v[64:67], v[36:39], v[12:15]
	v_mfma_f32_16x16x32_bf16 v[8:11], v[68:71], v[36:39], v[8:11]
	v_mfma_f32_16x16x32_bf16 v[4:7], v[72:75], v[36:39], v[4:7]
	v_mfma_f32_16x16x32_bf16 v[16:19], v[76:79], v[56:59], v[16:19]
	v_mfma_f32_16x16x32_bf16 v[12:15], v[80:83], v[56:59], v[12:15]
	v_mfma_f32_16x16x32_bf16 v[8:11], v[84:87], v[56:59], v[8:11]
	v_mfma_f32_16x16x32_bf16 v[4:7], v[88:91], v[56:59], v[4:7]
	s_nop 7
	v_mul_f32_e64 v36, v18, v18
	v_mul_f32_e64 v37, v19, v19
	v_pk_mul_f32 v[38:39], v[16:17], v[16:17]
	s_nop 0
	v_pk_mov_b32 v[44:45], v[38:39], v[36:37] op_sel:[1,0]
	v_mov_b32_e32 v39, v37
	v_pk_add_f32 v[36:37], v[44:45], v[38:39]
	v_pk_mul_f32 v[38:39], v[14:15], v[14:15]
	v_pk_mul_f32 v[44:45], v[12:13], v[12:13]
	v_pk_add_f32 v[36:37], v[36:37], v[36:37] op_sel:[0,1] op_sel_hi:[1,0]
	v_pk_mov_b32 v[46:47], v[44:45], v[38:39] op_sel:[1,0]
	v_mov_b32_e32 v45, v39
	v_pk_add_f32 v[38:39], v[46:47], v[44:45]
	v_mul_f32_e32 v44, v4, v4
	v_mul_f32_e32 v45, v5, v5
	v_pk_add_f32 v[38:39], v[38:39], v[38:39] op_sel:[0,1] op_sel_hi:[1,0]
	v_mov_b32_e32 v37, v44
	v_mov_b32_e32 v39, v45
	v_pk_add_f32 v[36:37], v[36:37], v[38:39]
	v_mul_f32_e32 v38, v9, v9
	v_mul_f32_e32 v44, v11, v11
	v_mul_f32_e32 v46, v6, v6
	v_mul_f32_e32 v47, v7, v7
	v_pk_fma_f32 v[38:39], v[8:9], v[8:9], v[38:39] op_sel_hi:[1,1,0]
	v_pk_fma_f32 v[44:45], v[10:11], v[10:11], v[44:45] op_sel_hi:[1,1,0]
	v_mov_b32_e32 v39, v46
	v_mov_b32_e32 v45, v47
	v_pk_add_f32 v[38:39], v[38:39], v[44:45]
	v_pk_add_f32 v[36:37], v[36:37], v[38:39]
	v_lshlrev_b64 v[38:39], 11, v[40:41]
	v_add_f32_e32 v36, v36, v37
	ds_bpermute_b32 v37, v42, v36
	s_waitcnt lgkmcnt(0)
	v_add_f32_e32 v36, v36, v37
	ds_bpermute_b32 v37, v43, v36
	s_waitcnt lgkmcnt(0)
	v_add_f32_e32 v36, v36, v37
	v_fmamk_f32 v36, v36, 0x3c800000, v176
	v_cmp_gt_f32_e32 vcc, s75, v36
	v_mul_f32_e32 v37, 0x4b800000, v36
	s_nop 0
	v_cndmask_b32_e32 v36, v36, v37, vcc
	v_rsq_f32_e32 v36, v36
	s_nop 0
	v_mul_f32_e32 v37, 0x45800000, v36
	v_cndmask_b32_e32 v44, v36, v37, vcc
	v_mad_i64_i32 v[36:37], s[8:9], v40, s61, v[32:33]
	v_lshl_add_u64 v[36:37], v[36:37], 0, s[90:91]
	v_lshl_add_u64 v[36:37], v[36:37], 0, v[34:35]
	v_mul_f32_e32 v16, v16, v44
	v_mul_f32_e32 v17, v17, v44
	s_add_u32 s8, s28, s90
	s_addc_u32 s9, s29, 0
	v_lshl_add_u64 v[38:39], s[8:9], 0, v[38:39]
	v_mul_f32_e32 v12, v12, v44
	v_mul_f32_e32 v13, v13, v44
	v_mul_f32_e32 v8, v8, v44
	v_mul_f32_e32 v9, v9, v44
	v_mul_f32_e32 v4, v4, v44
	v_mul_f32_e32 v5, v5, v44
	s_add_i32 s23, s23, s77
	s_add_i32 s22, s22, s27
	s_cmpk_gt_i32 s23, 0x3ff
	s_waitcnt vmcnt(0)
	v_mov_b32_e32 v46, v96
	v_mov_b32_e32 v47, v97
	v_mov_b32_e32 v48, v98
	v_mov_b32_e32 v49, v99
	v_mul_f32_e32 v16, v46, v16
	v_mul_f32_e32 v17, v47, v17
	v_mov_b32_e32 v40, v112
	v_mov_b32_e32 v41, v113
	v_lshlrev_b32_e32 v45, 16, v40
	v_and_b32_e32 v40, 0xffff0000, v40
	v_mul_f32_e32 v45, 0xbfb8aa3b, v45
	v_mul_f32_e32 v40, 0xbfb8aa3b, v40
	v_exp_f32_e32 v45, v45
	v_exp_f32_e32 v40, v40
	v_lshlrev_b32_e32 v50, 16, v41
	v_and_b32_e32 v41, 0xffff0000, v41
	v_mul_f32_e32 v50, 0xbfb8aa3b, v50
	v_mul_f32_e32 v41, 0xbfb8aa3b, v41
	v_exp_f32_e32 v50, v50
	v_exp_f32_e32 v41, v41
	v_add_f32_e32 v45, 1.0, v45
	v_add_f32_e32 v40, 1.0, v40
	v_rcp_f32_e32 v45, v45
	v_rcp_f32_e32 v40, v40
	v_add_f32_e32 v50, 1.0, v50
	v_add_f32_e32 v41, 1.0, v41
	v_rcp_f32_e32 v50, v50
	v_rcp_f32_e32 v41, v41
	v_mul_f32_e32 v16, v45, v16
	v_mul_f32_e32 v17, v40, v17
	v_cvt_pk_bf16_f32 v40, v16, v17
	v_mul_f32_e32 v16, v18, v44
	v_mul_f32_e32 v17, v19, v44
	v_mul_f32_e32 v16, v48, v16
	v_mul_f32_e32 v17, v49, v17
	v_mul_f32_e32 v16, v50, v16
	v_mul_f32_e32 v17, v41, v17
	v_cvt_pk_bf16_f32 v41, v16, v17
	v_lshl_add_u64 v[16:17], v[38:39], 0, v[34:35]
	global_store_dwordx2 v[16:17], v[40:41], off
	s_nop 0
	v_mov_b32_e32 v38, v100
	v_mov_b32_e32 v39, v101
	v_mov_b32_e32 v40, v102
	v_mov_b32_e32 v41, v103
	v_mov_b32_e32 v18, v114
	v_mov_b32_e32 v19, v115
	v_mul_f32_e32 v12, v38, v12
	v_lshlrev_b32_e32 v45, 16, v18
	v_and_b32_e32 v18, 0xffff0000, v18
	v_mul_f32_e32 v45, 0xbfb8aa3b, v45
	v_mul_f32_e32 v18, 0xbfb8aa3b, v18
	v_exp_f32_e32 v45, v45
	v_exp_f32_e32 v18, v18
	v_lshlrev_b32_e32 v46, 16, v19
	v_mul_f32_e32 v46, 0xbfb8aa3b, v46
	v_and_b32_e32 v19, 0xffff0000, v19
	v_exp_f32_e32 v46, v46
	v_mul_f32_e32 v19, 0xbfb8aa3b, v19
	v_add_f32_e32 v45, 1.0, v45
	v_add_f32_e32 v18, 1.0, v18
	v_exp_f32_e32 v19, v19
	v_rcp_f32_e32 v45, v45
	v_rcp_f32_e32 v18, v18
	v_add_f32_e32 v46, 1.0, v46
	v_rcp_f32_e32 v46, v46
	v_add_f32_e32 v19, 1.0, v19
	v_mul_f32_e32 v13, v39, v13
	v_rcp_f32_e32 v19, v19
	v_mul_f32_e32 v12, v12, v45
	v_mul_f32_e32 v13, v13, v18
	v_cvt_pk_bf16_f32 v12, v12, v13
	v_mul_f32_e32 v13, v14, v44
	v_mul_f32_e32 v13, v40, v13
	v_mul_f32_e32 v14, v15, v44
	v_mul_f32_e32 v13, v13, v46
	v_mul_f32_e32 v14, v41, v14
	v_mul_f32_e32 v14, v14, v19
	v_cvt_pk_bf16_f32 v13, v13, v14
	global_store_dwordx2 v[16:17], v[12:13], off offset:32
	s_nop 0
	v_mov_b32_e32 v18, v116
	v_mov_b32_e32 v19, v117
	v_mov_b32_e32 v14, v106
	v_mov_b32_e32 v15, v107
	v_mov_b32_e32 v12, v104
	v_mov_b32_e32 v13, v105
	v_mul_f32_e32 v8, v12, v8
	v_lshlrev_b32_e32 v38, 16, v18
	v_and_b32_e32 v18, 0xffff0000, v18
	v_mul_f32_e32 v38, 0xbfb8aa3b, v38
	v_mul_f32_e32 v18, 0xbfb8aa3b, v18
	v_exp_f32_e32 v38, v38
	v_exp_f32_e32 v18, v18
	v_lshlrev_b32_e32 v39, 16, v19
	v_mul_f32_e32 v39, 0xbfb8aa3b, v39
	v_and_b32_e32 v19, 0xffff0000, v19
	v_exp_f32_e32 v39, v39
	v_mul_f32_e32 v19, 0xbfb8aa3b, v19
	v_add_f32_e32 v38, 1.0, v38
	v_add_f32_e32 v18, 1.0, v18
	v_exp_f32_e32 v19, v19
	v_rcp_f32_e32 v38, v38
	v_rcp_f32_e32 v18, v18
	v_add_f32_e32 v39, 1.0, v39
	v_rcp_f32_e32 v39, v39
	v_add_f32_e32 v19, 1.0, v19
	v_mul_f32_e32 v9, v13, v9
	v_rcp_f32_e32 v19, v19
	v_mul_f32_e32 v8, v8, v38
	v_mul_f32_e32 v9, v9, v18
	v_cvt_pk_bf16_f32 v8, v8, v9
	v_mul_f32_e32 v9, v10, v44
	v_mul_f32_e32 v9, v14, v9
	v_mul_f32_e32 v10, v11, v44
	v_mul_f32_e32 v9, v9, v39
	v_mul_f32_e32 v10, v15, v10
	v_mul_f32_e32 v10, v10, v19
	v_cvt_pk_bf16_f32 v9, v9, v10
	global_store_dwordx2 v[16:17], v[8:9], off offset:64
	s_nop 0
	v_mov_b32_e32 v10, v110
	v_mov_b32_e32 v11, v111
	v_mov_b32_e32 v8, v108
	v_mov_b32_e32 v9, v109
	v_mov_b32_e32 v12, v118
	v_mov_b32_e32 v13, v119
	v_mul_f32_e32 v4, v4, v8
	v_lshlrev_b32_e32 v14, 16, v12
	v_and_b32_e32 v12, 0xffff0000, v12
	v_mul_f32_e32 v14, 0xbfb8aa3b, v14
	v_mul_f32_e32 v12, 0xbfb8aa3b, v12
	v_exp_f32_e32 v14, v14
	v_exp_f32_e32 v12, v12
	v_lshlrev_b32_e32 v15, 16, v13
	v_mul_f32_e32 v15, 0xbfb8aa3b, v15
	v_and_b32_e32 v13, 0xffff0000, v13
	v_exp_f32_e32 v15, v15
	v_mul_f32_e32 v13, 0xbfb8aa3b, v13
	v_add_f32_e32 v14, 1.0, v14
	v_add_f32_e32 v12, 1.0, v12
	v_exp_f32_e32 v13, v13
	v_rcp_f32_e32 v14, v14
	v_rcp_f32_e32 v12, v12
	v_add_f32_e32 v15, 1.0, v15
	v_rcp_f32_e32 v15, v15
	v_add_f32_e32 v13, 1.0, v13
	v_mul_f32_e32 v5, v5, v9
	v_rcp_f32_e32 v13, v13
	v_mul_f32_e32 v4, v4, v14
	v_mul_f32_e32 v5, v5, v12
	v_cvt_pk_bf16_f32 v4, v4, v5
	v_mul_f32_e32 v5, v6, v44
	v_mul_f32_e32 v5, v5, v10
	v_mul_f32_e32 v6, v7, v44
	v_mul_f32_e32 v5, v5, v15
	v_mul_f32_e32 v6, v6, v11
	v_mul_f32_e32 v6, v6, v13
	v_cvt_pk_bf16_f32 v5, v5, v6
	global_store_dwordx2 v[16:17], v[4:5], off offset:96
	s_cbranch_scc0 .LBB0_255
